# P0 conv loops: 4 sentinel loads + vmcnt(N+4) so waits do not block on previous stores
# baseline (speedup 1.0000x reference)
; __device__ __forceinline__ unsigned cvt_pk_bf16(float lo, float hi) { f32x2 v = {lo, hi}; bf16x2_t b = __builtin_convertvector(v, bf16x2_t); return __builtin_bit_cast(unsigned, b); }
; #define LAS __attribute__((address_space(3)))
; template <int MODE, int K, int N>
; __device__ __forceinline__ void conv_blocked(const float* __restrict__ W, bf16* D, const float* __restrict__ gk, unsigned gtid, unsigned nthr, LAS unsigned char* scr  ) {
;     ...
;     for (unsigned it = gtid; it < items; it += nthr) {
;         const unsigned kb = it / (unsigned)N; const int n = (int)(it - kb * (unsigned)N), k0 = (int)kb * 32;
;         if (MODE == 1 && n >= C_U && n < C_GB) continue;
;         const float* src = W + (size_t)k0 * N + n;
;         float v[32];
; #pragma unroll
;         for (int i = 0; i < 32; ++i) v[i] = __builtin_nontemporal_load(src + (size_t)i * N);
;         if (gk) {
; #pragma unroll
;             for (int i = 0; i < 32; ++i) v[i] *= gk[k0 + i];
;         }
;         const int rho = pg8::p32inv(lane & 31), half = lane >> 5;
; #pragma unroll
;         for (int c = 0; c < 4; ++c) { v4u o; o.x = cvt_pk_bf16(v[8 * c], v[8 * c + 1]); o.y = cvt_pk_bf16(v[8 * c + 2], v[8 * c + 3]); o.z = cvt_pk_bf16(v[8 * c + 4], v[8 * c + 5]); o.w = cvt_pk_bf16(v[8 * c + 6], v[8 * c + 7]);
;             *(LAS v4u*)(scr + (half * 32 + rho) * 64 + ((c * 16) ^ ((rho & 8) << 2))) = o; }
;         const int nb = n - lane;
; #pragma unroll
;         for (int i = 0; i < 4; ++i) { const int h2 = i >> 1, b2 = i & 1; const int gp = ((MODE == 1) ? nperm(nb + 32 * h2) : nb + 32 * h2) & ~31;
;             const v4u o = *(const LAS v4u*)(scr + (h2 * 32 + b2 * 16) * 64 + lane * 16);
;             *(v4u*)((unsigned char*)D + ((size_t)((gp >> 4) + b2) * (K >> 5) + (size_t)(k0 >> 5)) * 1024 + lane * 16) = o; }
;         asm volatile("s_waitcnt lgkmcnt(0)" ::: "memory");
;     }
.LBB0_37:
	v_and_b32_e32 v6, 0x3fe0000, v12
	v_and_b32_e32 v22, 0xfff, v13
	v_lshlrev_b32_e32 v6, 2, v6
	v_lshl_add_u64 v[14:15], s[42:43], 0, v[6:7]
	v_lshlrev_b32_e32 v6, 2, v22
	v_lshl_add_u64 v[14:15], v[14:15], 0, v[6:7]
	v_add_co_u32_e32 v16, vcc, 0x4000, v14
	global_load_dword v23, v[14:15], off nt
	s_nop 0
	v_addc_co_u32_e32 v17, vcc, 0, v15, vcc
	v_add_co_u32_e32 v18, vcc, 0x8000, v14
	global_load_dword v24, v[16:17], off nt
	s_nop 0
	v_addc_co_u32_e32 v19, vcc, 0, v15, vcc
	v_add_co_u32_e32 v16, vcc, 0xc000, v14
	v_lshrrev_b32_e32 v6, 2, v13
	s_nop 0
	v_addc_co_u32_e32 v17, vcc, 0, v15, vcc
	v_add_co_u32_e32 v20, vcc, 0x10000, v14
	global_load_dword v25, v[18:19], off nt
	global_load_dword v26, v[16:17], off nt
	v_addc_co_u32_e32 v21, vcc, 0, v15, vcc
	v_add_co_u32_e32 v16, vcc, 0x14000, v14
	v_and_b32_e32 v6, 0x7fc00, v6
	s_nop 0
	v_addc_co_u32_e32 v17, vcc, 0, v15, vcc
	v_add_co_u32_e32 v18, vcc, 0x18000, v14
	global_load_dword v27, v[20:21], off nt
	global_load_dword v28, v[16:17], off nt
	v_addc_co_u32_e32 v19, vcc, 0, v15, vcc
	v_add_co_u32_e32 v16, vcc, 0x1c000, v14
	v_lshl_add_u64 v[30:31], v[10:11], 0, v[6:7]
	s_nop 0
	v_addc_co_u32_e32 v17, vcc, 0, v15, vcc
	v_add_co_u32_e32 v20, vcc, 0x20000, v14
	global_load_dword v29, v[18:19], off nt
	global_load_dword v40, v[16:17], off nt
	v_addc_co_u32_e32 v21, vcc, 0, v15, vcc
	v_add_co_u32_e32 v16, vcc, 0x24000, v14
	v_add_u32_e32 v13, s0, v13
	s_nop 0
	v_addc_co_u32_e32 v17, vcc, 0, v15, vcc
	v_add_co_u32_e32 v18, vcc, 0x28000, v14
	global_load_dword v41, v[20:21], off nt
	global_load_dword v42, v[16:17], off nt
	v_addc_co_u32_e32 v19, vcc, 0, v15, vcc
	v_add_co_u32_e32 v16, vcc, 0x2c000, v14
	v_add_u32_e32 v12, s62, v12
	s_nop 0
	v_addc_co_u32_e32 v17, vcc, 0, v15, vcc
	v_add_co_u32_e32 v20, vcc, 0x30000, v14
	global_load_dword v43, v[18:19], off nt
	global_load_dword v49, v[16:17], off nt
	v_addc_co_u32_e32 v21, vcc, 0, v15, vcc
	v_add_co_u32_e32 v16, vcc, 0x34000, v14
	s_nop 1
	v_addc_co_u32_e32 v17, vcc, 0, v15, vcc
	v_add_co_u32_e32 v18, vcc, 0x38000, v14
	global_load_dword v50, v[20:21], off nt
	global_load_dword v51, v[16:17], off nt
	v_addc_co_u32_e32 v19, vcc, 0, v15, vcc
	v_add_co_u32_e32 v16, vcc, 0x3c000, v14
	s_nop 1
	v_addc_co_u32_e32 v17, vcc, 0, v15, vcc
	v_add_co_u32_e32 v20, vcc, 0x40000, v14
	global_load_dword v52, v[18:19], off nt
	global_load_dword v53, v[16:17], off nt
	v_addc_co_u32_e32 v21, vcc, 0, v15, vcc
	v_add_co_u32_e32 v16, vcc, 0x44000, v14
	s_nop 1
	v_addc_co_u32_e32 v17, vcc, 0, v15, vcc
	v_add_co_u32_e32 v18, vcc, 0x48000, v14
	global_load_dword v54, v[20:21], off nt
	global_load_dword v55, v[16:17], off nt
	v_addc_co_u32_e32 v19, vcc, 0, v15, vcc
	v_add_co_u32_e32 v16, vcc, 0x4c000, v14
	s_nop 1
	v_addc_co_u32_e32 v17, vcc, 0, v15, vcc
	v_add_co_u32_e32 v20, vcc, 0x50000, v14
	global_load_dword v56, v[18:19], off nt
	global_load_dword v57, v[16:17], off nt
	v_addc_co_u32_e32 v21, vcc, 0, v15, vcc
	v_add_co_u32_e32 v16, vcc, 0x54000, v14
	s_nop 1
	v_addc_co_u32_e32 v17, vcc, 0, v15, vcc
	v_add_co_u32_e32 v18, vcc, 0x58000, v14
	global_load_dword v58, v[20:21], off nt
	global_load_dword v59, v[16:17], off nt
	v_addc_co_u32_e32 v19, vcc, 0, v15, vcc
	v_add_co_u32_e32 v16, vcc, 0x5c000, v14
	s_nop 1
	v_addc_co_u32_e32 v17, vcc, 0, v15, vcc
	v_add_co_u32_e32 v20, vcc, 0x60000, v14
	global_load_dword v60, v[18:19], off nt
	global_load_dword v61, v[16:17], off nt
	v_addc_co_u32_e32 v21, vcc, 0, v15, vcc
	v_add_co_u32_e32 v16, vcc, 0x64000, v14
	s_nop 1
	v_addc_co_u32_e32 v17, vcc, 0, v15, vcc
	v_add_co_u32_e32 v18, vcc, 0x68000, v14
	global_load_dword v62, v[20:21], off nt
	global_load_dword v63, v[16:17], off nt
	v_addc_co_u32_e32 v19, vcc, 0, v15, vcc
	v_add_co_u32_e32 v16, vcc, 0x6c000, v14
	s_nop 1
	v_addc_co_u32_e32 v17, vcc, 0, v15, vcc
	v_add_co_u32_e32 v20, vcc, 0x70000, v14
	global_load_dword v64, v[18:19], off nt
	global_load_dword v65, v[16:17], off nt
	v_addc_co_u32_e32 v21, vcc, 0, v15, vcc
	v_add_co_u32_e32 v16, vcc, 0x74000, v14
	s_nop 1
	v_addc_co_u32_e32 v17, vcc, 0, v15, vcc
	v_add_co_u32_e32 v18, vcc, 0x78000, v14
	global_load_dword v66, v[20:21], off nt
	global_load_dword v67, v[16:17], off nt
	v_addc_co_u32_e32 v19, vcc, 0, v15, vcc
	v_add_co_u32_e32 v14, vcc, 0x7c000, v14
	s_nop 1
	v_addc_co_u32_e32 v15, vcc, 0, v15, vcc
	global_load_dword v68, v[18:19], off nt
	global_load_dword v69, v[14:15], off nt
	global_load_dword v120, v[14:15], off nt
	global_load_dword v120, v[14:15], off nt
	global_load_dword v120, v[14:15], off nt
	global_load_dword v120, v[14:15], off nt
	v_sub_u32_e32 v14, v22, v2
	v_ashrrev_i32_e32 v15, 4, v14
	v_add_u32_e32 v17, 32, v14
	v_and_b32_e32 v14, -2, v15
	v_ashrrev_i32_e32 v19, 4, v17
	v_or_b32_e32 v16, 1, v15
	v_ashrrev_i32_e32 v15, 31, v14
	v_and_b32_e32 v18, -2, v19
	v_ashrrev_i32_e32 v17, 31, v16
	v_or_b32_e32 v20, 1, v19
	v_lshlrev_b64 v[14:15], 19, v[14:15]
	v_ashrrev_i32_e32 v19, 31, v18
	v_lshlrev_b64 v[16:17], 19, v[16:17]
	v_lshl_add_u64 v[32:33], v[30:31], 0, v[14:15]
	v_lshlrev_b64 v[14:15], 19, v[18:19]
	v_lshl_add_u64 v[34:35], v[30:31], 0, v[16:17]
	v_lshl_add_u64 v[38:39], v[30:31], 0, v[14:15]
	s_waitcnt vmcnt(34)
	v_cvt_pk_bf16_f32 v14, v23, v24
	s_waitcnt vmcnt(32)
	v_cvt_pk_bf16_f32 v15, v25, v26
	s_waitcnt vmcnt(30)
	v_cvt_pk_bf16_f32 v16, v27, v28
	s_waitcnt vmcnt(28)
	v_cvt_pk_bf16_f32 v17, v29, v40
	ds_write_b128 v45, v[14:17]
	s_waitcnt vmcnt(26)
	v_cvt_pk_bf16_f32 v14, v41, v42
	s_waitcnt vmcnt(24)
	v_cvt_pk_bf16_f32 v15, v43, v49
	s_waitcnt vmcnt(22)
	v_cvt_pk_bf16_f32 v16, v50, v51
	s_waitcnt vmcnt(20)
	v_cvt_pk_bf16_f32 v17, v52, v53
	ds_write_b128 v45, v[14:17] offset:16
	s_waitcnt vmcnt(18)
	v_cvt_pk_bf16_f32 v14, v54, v55
	s_waitcnt vmcnt(16)
	v_cvt_pk_bf16_f32 v15, v56, v57
	v_ashrrev_i32_e32 v21, 31, v20
	v_lshlrev_b64 v[36:37], 19, v[20:21]
	s_waitcnt vmcnt(14)
	v_cvt_pk_bf16_f32 v16, v58, v59
	v_lshl_add_u64 v[30:31], v[30:31], 0, v[36:37]
	v_cmp_lt_u32_e32 vcc, s63, v13
	s_or_b64 s[46:47], vcc, s[46:47]
	s_waitcnt vmcnt(12)
	v_cvt_pk_bf16_f32 v17, v60, v61
	ds_write_b128 v46, v[14:17]
	s_waitcnt vmcnt(10)
	v_cvt_pk_bf16_f32 v14, v62, v63
	s_waitcnt vmcnt(8)
	v_cvt_pk_bf16_f32 v15, v64, v65
	s_waitcnt vmcnt(6)
	v_cvt_pk_bf16_f32 v16, v66, v67
	s_waitcnt vmcnt(4)
	v_cvt_pk_bf16_f32 v17, v68, v69
	ds_write_b128 v46, v[14:17] offset:16
	ds_read_b128 v[14:17], v47
	ds_read_b128 v[18:21], v47 offset:1024
	ds_read_b128 v[22:25], v47 offset:2048
	ds_read_b128 v[26:29], v47 offset:3072
	s_waitcnt lgkmcnt(3)
	global_store_dwordx4 v[32:33], v[14:17], off
	s_waitcnt lgkmcnt(2)
	global_store_dwordx4 v[34:35], v[18:21], off
	s_waitcnt lgkmcnt(1)
	global_store_dwordx4 v[38:39], v[22:25], off
	s_waitcnt lgkmcnt(0)
	global_store_dwordx4 v[30:31], v[26:29], off
	s_waitcnt lgkmcnt(0)
	s_andn2_b64 exec, exec, s[46:47]
	s_cbranch_execnz .LBB0_37

; __device__ __forceinline__ unsigned cvt_pk_bf16(float lo, float hi) { f32x2 v = {lo, hi}; bf16x2_t b = __builtin_convertvector(v, bf16x2_t); return __builtin_bit_cast(unsigned, b); }
; #define LAS __attribute__((address_space(3)))
; template <int MODE, int K, int N>
; __device__ __forceinline__ void conv_blocked(const float* __restrict__ W, bf16* D, const float* __restrict__ gk, unsigned gtid, unsigned nthr, LAS unsigned char* scr  ) {
;     ...
;         const int rho = pg8::p32inv(lane & 31), half = lane >> 5;
; #pragma unroll
;         for (int c = 0; c < 4; ++c) { v4u o; o.x = cvt_pk_bf16(v[8 * c], v[8 * c + 1]); o.y = cvt_pk_bf16(v[8 * c + 2], v[8 * c + 3]); o.z = cvt_pk_bf16(v[8 * c + 4], v[8 * c + 5]); o.w = cvt_pk_bf16(v[8 * c + 6], v[8 * c + 7]);
;             *(LAS v4u*)(scr + (half * 32 + rho) * 64 + ((c * 16) ^ ((rho & 8) << 2))) = o; }
;         const int nb = n - lane;
; #pragma unroll
;         for (int i = 0; i < 4; ++i) { const int h2 = i >> 1, b2 = i & 1; const int gp = ((MODE == 1) ? nperm(nb + 32 * h2) : nb + 32 * h2) & ~31;
;             const v4u o = *(const LAS v4u*)(scr + (h2 * 32 + b2 * 16) * 64 + lane * 16);
;             *(v4u*)((unsigned char*)D + ((size_t)((gp >> 4) + b2) * (K >> 5) + (size_t)(k0 >> 5)) * 1024 + lane * 16) = o; }
;         asm volatile("s_waitcnt lgkmcnt(0)" ::: "memory");
;     }
.Lsent2_nogk:
	global_load_dword v120, v[62:63], off nt
	global_load_dword v120, v[62:63], off nt
	global_load_dword v120, v[62:63], off nt
	global_load_dword v120, v[62:63], off nt
.LBB0_40:
	s_waitcnt vmcnt(34)
	v_cvt_pk_bf16_f32 v12, v12, v13
	s_waitcnt vmcnt(32)
	v_cvt_pk_bf16_f32 v13, v14, v15
	s_waitcnt vmcnt(30)
	v_cvt_pk_bf16_f32 v14, v16, v17
	s_waitcnt vmcnt(28)
	v_cvt_pk_bf16_f32 v15, v18, v19
	ds_write_b128 v45, v[12:15]
	s_waitcnt vmcnt(26)
	v_cvt_pk_bf16_f32 v12, v20, v21
	s_waitcnt vmcnt(24)
	v_cvt_pk_bf16_f32 v13, v22, v23
	s_waitcnt vmcnt(22)
	v_cvt_pk_bf16_f32 v14, v24, v25
	s_waitcnt vmcnt(20)
	v_cvt_pk_bf16_f32 v15, v26, v27
	ds_write_b128 v45, v[12:15] offset:16
	s_waitcnt vmcnt(18)
	v_cvt_pk_bf16_f32 v12, v28, v29
	s_waitcnt vmcnt(16)
	v_cvt_pk_bf16_f32 v13, v30, v31
	s_waitcnt vmcnt(14)
	v_cvt_pk_bf16_f32 v14, v32, v33
	s_waitcnt vmcnt(12)
	v_cvt_pk_bf16_f32 v15, v34, v35
	ds_write_b128 v46, v[12:15]
	s_waitcnt vmcnt(10)
	v_cvt_pk_bf16_f32 v12, v36, v37
	s_waitcnt vmcnt(8)
	v_cvt_pk_bf16_f32 v13, v38, v39
	s_waitcnt vmcnt(6)
	v_cvt_pk_bf16_f32 v14, v42, v43
	s_waitcnt vmcnt(4)
	v_cvt_pk_bf16_f32 v15, v40, v41
	v_lshrrev_b32_e32 v6, 4, v49
	ds_write_b128 v46, v[12:15] offset:16
	v_sub_u32_e32 v24, v50, v2
	v_and_b32_e32 v6, 0x1fc00, v6
	v_lshl_add_u64 v[20:21], v[10:11], 0, v[6:7]
	ds_read_b128 v[12:15], v47
	v_ashrrev_i32_e32 v6, 4, v24
	v_and_b32_e32 v16, -2, v6
	v_ashrrev_i32_e32 v17, 31, v16
	v_lshlrev_b64 v[16:17], 17, v[16:17]
	v_lshl_add_u64 v[22:23], v[20:21], 0, v[16:17]
	ds_read_b128 v[16:19], v47 offset:1024
	s_waitcnt lgkmcnt(1)
	global_store_dwordx4 v[22:23], v[12:15], off
	v_add_u32_e32 v49, s0, v49
	v_cmp_lt_u32_e32 vcc, s63, v49
	v_or_b32_e32 v12, 1, v6
	v_ashrrev_i32_e32 v13, 31, v12
	v_lshlrev_b64 v[12:13], 17, v[12:13]
	v_lshl_add_u64 v[12:13], v[20:21], 0, v[12:13]
	v_add_u32_e32 v6, 32, v24
	s_waitcnt lgkmcnt(0)
	global_store_dwordx4 v[12:13], v[16:19], off
	ds_read_b128 v[12:15], v47 offset:2048
	v_ashrrev_i32_e32 v6, 4, v6
	v_and_b32_e32 v16, -2, v6
	v_ashrrev_i32_e32 v17, 31, v16
	v_lshlrev_b64 v[16:17], 17, v[16:17]
	v_lshl_add_u64 v[22:23], v[20:21], 0, v[16:17]
	ds_read_b128 v[16:19], v47 offset:3072
	s_waitcnt lgkmcnt(1)
	global_store_dwordx4 v[22:23], v[12:15], off
	s_or_b64 s[48:49], vcc, s[48:49]
	s_nop 0
	v_or_b32_e32 v12, 1, v6
	v_ashrrev_i32_e32 v13, 31, v12
	v_lshlrev_b64 v[12:13], 17, v[12:13]
	v_lshl_add_u64 v[12:13], v[20:21], 0, v[12:13]
	s_waitcnt lgkmcnt(0)
	global_store_dwordx4 v[12:13], v[16:19], off
	s_waitcnt lgkmcnt(0)
	s_andn2_b64 exec, exec, s[48:49]
	s_cbranch_execz .LBB0_43
; template <int MODE, int K, int N>
; __device__ __forceinline__ void conv_blocked(const float* __restrict__ W, bf16* D, const float* __restrict__ gk, unsigned gtid, unsigned nthr, LAS unsigned char* scr  ) {
;     ...
;         const unsigned kb = it / (unsigned)N; const int n = (int)(it - kb * (unsigned)N), k0 = (int)kb * 32;
;         if (MODE == 1 && n >= C_U && n < C_GB) continue;
;         const float* src = W + (size_t)k0 * N + n;
;         float v[32];
; #pragma unroll
;         for (int i = 0; i < 32; ++i) v[i] = __builtin_nontemporal_load(src + (size_t)i * N);
;         if (gk) {
; #pragma unroll
;             for (int i = 0; i < 32; ++i) v[i] *= gk[k0 + i];
;         }
.LBB0_41:
	v_lshrrev_b32_e32 v51, 9, v49
	v_and_b32_e32 v52, 0xfe0, v51
	v_and_b32_e32 v50, 0x3fff, v49
	v_lshlrev_b32_e32 v6, 16, v52
	v_lshl_add_u64 v[12:13], s[44:45], 0, v[6:7]
	v_lshlrev_b32_e32 v6, 2, v50
	v_lshl_add_u64 v[36:37], v[12:13], 0, v[6:7]
	v_add_co_u32_e32 v14, vcc, 0x10000, v36
	s_nop 1
	v_addc_co_u32_e32 v15, vcc, 0, v37, vcc
	v_add_co_u32_e32 v16, vcc, 0x20000, v36
	s_nop 1
	v_addc_co_u32_e32 v17, vcc, 0, v37, vcc
	v_add_co_u32_e32 v18, vcc, 0x30000, v36
	s_nop 1
	v_addc_co_u32_e32 v19, vcc, 0, v37, vcc
	v_add_co_u32_e32 v20, vcc, 0x40000, v36
	s_nop 1
	v_addc_co_u32_e32 v21, vcc, 0, v37, vcc
	v_add_co_u32_e32 v22, vcc, 0x50000, v36
	s_nop 1
	v_addc_co_u32_e32 v23, vcc, 0, v37, vcc
	v_add_co_u32_e32 v24, vcc, 0x60000, v36
	s_nop 1
	v_addc_co_u32_e32 v25, vcc, 0, v37, vcc
	v_add_co_u32_e32 v26, vcc, 0x70000, v36
	s_nop 1
	v_addc_co_u32_e32 v27, vcc, 0, v37, vcc
	global_load_dword v12, v[36:37], off nt
	global_load_dword v13, v[14:15], off nt
	s_nop 0
	global_load_dword v14, v[16:17], off nt
	global_load_dword v15, v[18:19], off nt
	s_nop 0
	global_load_dword v16, v[20:21], off nt
	global_load_dword v17, v[22:23], off nt
	global_load_dword v18, v[24:25], off nt
	global_load_dword v19, v[26:27], off nt
	v_add_co_u32_e32 v20, vcc, s60, v36
	s_nop 1
	v_addc_co_u32_e32 v21, vcc, 0, v37, vcc
	v_add_co_u32_e32 v22, vcc, 0x90000, v36
	s_nop 1
	v_addc_co_u32_e32 v23, vcc, 0, v37, vcc
	v_add_co_u32_e32 v24, vcc, 0xa0000, v36
	s_nop 1
	v_addc_co_u32_e32 v25, vcc, 0, v37, vcc
	v_add_co_u32_e32 v26, vcc, 0xb0000, v36
	s_nop 1
	v_addc_co_u32_e32 v27, vcc, 0, v37, vcc
	v_add_co_u32_e32 v28, vcc, 0xc0000, v36
	s_nop 1
	v_addc_co_u32_e32 v29, vcc, 0, v37, vcc
	v_add_co_u32_e32 v30, vcc, 0xd0000, v36
	s_nop 1
	v_addc_co_u32_e32 v31, vcc, 0, v37, vcc
	v_add_co_u32_e32 v32, vcc, 0xe0000, v36
	s_nop 1
	v_addc_co_u32_e32 v33, vcc, 0, v37, vcc
	v_add_co_u32_e32 v34, vcc, 0xf0000, v36
	s_nop 1
	v_addc_co_u32_e32 v35, vcc, 0, v37, vcc
	global_load_dword v20, v[20:21], off nt
	s_nop 0
	global_load_dword v21, v[22:23], off nt
	s_nop 0
	global_load_dword v22, v[24:25], off nt
	global_load_dword v23, v[26:27], off nt
	s_nop 0
	global_load_dword v24, v[28:29], off nt
	global_load_dword v25, v[30:31], off nt
	global_load_dword v26, v[32:33], off nt
	global_load_dword v27, v[34:35], off nt
	v_add_co_u32_e32 v28, vcc, 0x100000, v36
	s_nop 1
	v_addc_co_u32_e32 v29, vcc, 0, v37, vcc
	v_add_co_u32_e32 v30, vcc, 0x110000, v36
	s_nop 1
	v_addc_co_u32_e32 v31, vcc, 0, v37, vcc
	v_add_co_u32_e32 v32, vcc, 0x120000, v36
	s_nop 1
	v_addc_co_u32_e32 v33, vcc, 0, v37, vcc
	v_add_co_u32_e32 v34, vcc, 0x130000, v36
	s_nop 1
	v_addc_co_u32_e32 v35, vcc, 0, v37, vcc
	v_add_co_u32_e32 v38, vcc, s61, v36
	s_nop 1
	v_addc_co_u32_e32 v39, vcc, 0, v37, vcc
	v_add_co_u32_e32 v40, vcc, 0x150000, v36
	s_nop 1
	v_addc_co_u32_e32 v41, vcc, 0, v37, vcc
	v_add_co_u32_e32 v42, vcc, 0x160000, v36
	s_nop 1
	v_addc_co_u32_e32 v43, vcc, 0, v37, vcc
	v_add_co_u32_e32 v54, vcc, 0x170000, v36
	s_nop 1
	v_addc_co_u32_e32 v55, vcc, 0, v37, vcc
	global_load_dword v28, v[28:29], off nt
	s_nop 0
	global_load_dword v29, v[30:31], off nt
	s_nop 0
	global_load_dword v30, v[32:33], off nt
	global_load_dword v31, v[34:35], off nt
	s_nop 0
	global_load_dword v32, v[38:39], off nt
	global_load_dword v33, v[40:41], off nt
	global_load_dword v34, v[42:43], off nt
	global_load_dword v35, v[54:55], off nt
	v_add_co_u32_e32 v38, vcc, 0x180000, v36
	s_nop 1
	v_addc_co_u32_e32 v39, vcc, 0, v37, vcc
	v_add_co_u32_e32 v40, vcc, 0x190000, v36
	s_nop 1
	v_addc_co_u32_e32 v41, vcc, 0, v37, vcc
	v_add_co_u32_e32 v42, vcc, 0x1a0000, v36
	s_nop 1
	v_addc_co_u32_e32 v43, vcc, 0, v37, vcc
	v_add_co_u32_e32 v54, vcc, 0x1b0000, v36
	s_nop 1
	v_addc_co_u32_e32 v55, vcc, 0, v37, vcc
	v_add_co_u32_e32 v56, vcc, 0x1c0000, v36
	s_nop 1
	v_addc_co_u32_e32 v57, vcc, 0, v37, vcc
	v_add_co_u32_e32 v58, vcc, 0x1d0000, v36
	s_nop 1
	v_addc_co_u32_e32 v59, vcc, 0, v37, vcc
	v_add_co_u32_e32 v60, vcc, 0x1e0000, v36
	s_nop 1
	v_addc_co_u32_e32 v61, vcc, 0, v37, vcc
	v_add_co_u32_e32 v62, vcc, 0x1f0000, v36
	s_nop 1
	v_addc_co_u32_e32 v63, vcc, 0, v37, vcc
	global_load_dword v36, v[38:39], off nt
	global_load_dword v37, v[40:41], off nt
	s_nop 0
	global_load_dword v38, v[42:43], off nt
	global_load_dword v39, v[54:55], off nt
	s_nop 0
	global_load_dword v42, v[56:57], off nt
	global_load_dword v43, v[58:59], off nt
	global_load_dword v40, v[60:61], off nt
	global_load_dword v41, v[62:63], off nt
	s_andn2_b64 vcc, exec, s[30:31]
	s_cbranch_vccnz .Lsent2_nogk
	v_lshlrev_b32_e32 v6, 2, v52
	global_load_dwordx3 v[80:82], v6, s[46:47] offset:112
	global_load_dwordx4 v[52:55], v6, s[46:47]
	global_load_dwordx4 v[56:59], v6, s[46:47] offset:16
	global_load_dwordx4 v[60:63], v6, s[46:47] offset:32
	global_load_dwordx4 v[64:67], v6, s[46:47] offset:48
	global_load_dwordx4 v[68:71], v6, s[46:47] offset:64
	global_load_dwordx4 v[72:75], v6, s[46:47] offset:80
	global_load_dwordx4 v[76:79], v6, s[46:47] offset:96
	v_lshl_or_b32 v6, v51, 2, v48
	global_load_dword v83, v6, s[46:47]
	global_load_dword v120, v6, s[46:47]
	global_load_dword v120, v6, s[46:47]
	global_load_dword v120, v6, s[46:47]
	global_load_dword v120, v6, s[46:47]
	s_waitcnt vmcnt(12)
	v_pk_mul_f32 v[42:43], v[42:43], v[80:81]
	s_waitcnt vmcnt(11)
	v_pk_mul_f32 v[12:13], v[12:13], v[52:53]
	v_pk_mul_f32 v[14:15], v[14:15], v[54:55]
	s_waitcnt vmcnt(10)
	v_pk_mul_f32 v[16:17], v[16:17], v[56:57]
	v_pk_mul_f32 v[18:19], v[18:19], v[58:59]
	s_waitcnt vmcnt(9)
	v_pk_mul_f32 v[20:21], v[20:21], v[60:61]
	v_pk_mul_f32 v[22:23], v[22:23], v[62:63]
	s_waitcnt vmcnt(8)
	v_pk_mul_f32 v[24:25], v[24:25], v[64:65]
	v_pk_mul_f32 v[26:27], v[26:27], v[66:67]
	s_waitcnt vmcnt(7)
	v_pk_mul_f32 v[28:29], v[28:29], v[68:69]
	v_pk_mul_f32 v[30:31], v[30:31], v[70:71]
	s_waitcnt vmcnt(6)
	v_pk_mul_f32 v[32:33], v[32:33], v[72:73]
	v_pk_mul_f32 v[34:35], v[34:35], v[74:75]
	s_waitcnt vmcnt(5)
	v_pk_mul_f32 v[36:37], v[36:37], v[76:77]
	v_pk_mul_f32 v[38:39], v[38:39], v[78:79]
	s_waitcnt vmcnt(4)
	v_pk_mul_f32 v[40:41], v[40:41], v[82:83]
	s_branch .LBB0_40

; __device__ __forceinline__ unsigned cvt_pk_bf16(float lo, float hi) { f32x2 v = {lo, hi}; bf16x2_t b = __builtin_convertvector(v, bf16x2_t); return __builtin_bit_cast(unsigned, b); }
; #define LAS __attribute__((address_space(3)))
; template <int MODE, int K, int N>
; __device__ __forceinline__ void conv_blocked(const float* __restrict__ W, bf16* D, const float* __restrict__ gk, unsigned gtid, unsigned nthr, LAS unsigned char* scr  ) {
;     ...
;     for (unsigned it = gtid; it < items; it += nthr) {
;         const unsigned kb = it / (unsigned)N; const int n = (int)(it - kb * (unsigned)N), k0 = (int)kb * 32;
;         if (MODE == 1 && n >= C_U && n < C_GB) continue;
;         const float* src = W + (size_t)k0 * N + n;
;         float v[32];
; #pragma unroll
;         for (int i = 0; i < 32; ++i) v[i] = __builtin_nontemporal_load(src + (size_t)i * N);
;         if (gk) {
; #pragma unroll
;             for (int i = 0; i < 32; ++i) v[i] *= gk[k0 + i];
;         }
;         const int rho = pg8::p32inv(lane & 31), half = lane >> 5;
; #pragma unroll
;         for (int c = 0; c < 4; ++c) { v4u o; o.x = cvt_pk_bf16(v[8 * c], v[8 * c + 1]); o.y = cvt_pk_bf16(v[8 * c + 2], v[8 * c + 3]); o.z = cvt_pk_bf16(v[8 * c + 4], v[8 * c + 5]); o.w = cvt_pk_bf16(v[8 * c + 6], v[8 * c + 7]);
;             *(LAS v4u*)(scr + (half * 32 + rho) * 64 + ((c * 16) ^ ((rho & 8) << 2))) = o; }
;         const int nb = n - lane;
; #pragma unroll
;         for (int i = 0; i < 4; ++i) { const int h2 = i >> 1, b2 = i & 1; const int gp = ((MODE == 1) ? nperm(nb + 32 * h2) : nb + 32 * h2) & ~31;
;             const v4u o = *(const LAS v4u*)(scr + (h2 * 32 + b2 * 16) * 64 + lane * 16);
;             *(v4u*)((unsigned char*)D + ((size_t)((gp >> 4) + b2) * (K >> 5) + (size_t)(k0 >> 5)) * 1024 + lane * 16) = o; }
;         asm volatile("s_waitcnt lgkmcnt(0)" ::: "memory");
;     }
.LBB0_45:
	v_and_b32_e32 v6, 0xfe0000, v12
	v_and_b32_e32 v22, 0xfff, v13
	v_lshlrev_b32_e32 v6, 2, v6
	v_lshl_add_u64 v[14:15], s[44:45], 0, v[6:7]
	v_lshlrev_b32_e32 v6, 2, v22
	v_lshl_add_u64 v[14:15], v[14:15], 0, v[6:7]
	v_add_co_u32_e32 v16, vcc, 0x4000, v14
	global_load_dword v23, v[14:15], off nt
	s_nop 0
	v_addc_co_u32_e32 v17, vcc, 0, v15, vcc
	v_add_co_u32_e32 v18, vcc, 0x8000, v14
	global_load_dword v24, v[16:17], off nt
	s_nop 0
	v_addc_co_u32_e32 v19, vcc, 0, v15, vcc
	v_add_co_u32_e32 v16, vcc, 0xc000, v14
	v_lshrrev_b32_e32 v6, 2, v13
	s_nop 0
	v_addc_co_u32_e32 v17, vcc, 0, v15, vcc
	v_add_co_u32_e32 v20, vcc, 0x10000, v14
	global_load_dword v25, v[18:19], off nt
	global_load_dword v26, v[16:17], off nt
	v_addc_co_u32_e32 v21, vcc, 0, v15, vcc
	v_add_co_u32_e32 v16, vcc, 0x14000, v14
	v_and_b32_e32 v6, 0x1fc00, v6
	s_nop 0
	v_addc_co_u32_e32 v17, vcc, 0, v15, vcc
	v_add_co_u32_e32 v18, vcc, 0x18000, v14
	global_load_dword v27, v[20:21], off nt
	global_load_dword v28, v[16:17], off nt
	v_addc_co_u32_e32 v19, vcc, 0, v15, vcc
	v_add_co_u32_e32 v16, vcc, 0x1c000, v14
	v_lshl_add_u64 v[30:31], v[10:11], 0, v[6:7]
	s_nop 0
	v_addc_co_u32_e32 v17, vcc, 0, v15, vcc
	v_add_co_u32_e32 v20, vcc, 0x20000, v14
	global_load_dword v29, v[18:19], off nt
	global_load_dword v40, v[16:17], off nt
	v_addc_co_u32_e32 v21, vcc, 0, v15, vcc
	v_add_co_u32_e32 v16, vcc, 0x24000, v14
	v_add_u32_e32 v13, s0, v13
	s_nop 0
	v_addc_co_u32_e32 v17, vcc, 0, v15, vcc
	v_add_co_u32_e32 v18, vcc, 0x28000, v14
	global_load_dword v41, v[20:21], off nt
	global_load_dword v42, v[16:17], off nt
	v_addc_co_u32_e32 v19, vcc, 0, v15, vcc
	v_add_co_u32_e32 v16, vcc, 0x2c000, v14
	v_add_u32_e32 v12, s62, v12
	s_nop 0
	v_addc_co_u32_e32 v17, vcc, 0, v15, vcc
	v_add_co_u32_e32 v20, vcc, 0x30000, v14
	global_load_dword v43, v[18:19], off nt
	global_load_dword v49, v[16:17], off nt
	v_addc_co_u32_e32 v21, vcc, 0, v15, vcc
	v_add_co_u32_e32 v16, vcc, 0x34000, v14
	s_nop 1
	v_addc_co_u32_e32 v17, vcc, 0, v15, vcc
	v_add_co_u32_e32 v18, vcc, 0x38000, v14
	global_load_dword v50, v[20:21], off nt
	global_load_dword v51, v[16:17], off nt
	v_addc_co_u32_e32 v19, vcc, 0, v15, vcc
	v_add_co_u32_e32 v16, vcc, 0x3c000, v14
	s_nop 1
	v_addc_co_u32_e32 v17, vcc, 0, v15, vcc
	v_add_co_u32_e32 v20, vcc, 0x40000, v14
	global_load_dword v52, v[18:19], off nt
	global_load_dword v53, v[16:17], off nt
	v_addc_co_u32_e32 v21, vcc, 0, v15, vcc
	v_add_co_u32_e32 v16, vcc, 0x44000, v14
	s_nop 1
	v_addc_co_u32_e32 v17, vcc, 0, v15, vcc
	v_add_co_u32_e32 v18, vcc, 0x48000, v14
	global_load_dword v54, v[20:21], off nt
	global_load_dword v55, v[16:17], off nt
	v_addc_co_u32_e32 v19, vcc, 0, v15, vcc
	v_add_co_u32_e32 v16, vcc, 0x4c000, v14
	s_nop 1
	v_addc_co_u32_e32 v17, vcc, 0, v15, vcc
	v_add_co_u32_e32 v20, vcc, 0x50000, v14
	global_load_dword v56, v[18:19], off nt
	global_load_dword v57, v[16:17], off nt
	v_addc_co_u32_e32 v21, vcc, 0, v15, vcc
	v_add_co_u32_e32 v16, vcc, 0x54000, v14
	s_nop 1
	v_addc_co_u32_e32 v17, vcc, 0, v15, vcc
	v_add_co_u32_e32 v18, vcc, 0x58000, v14
	global_load_dword v58, v[20:21], off nt
	global_load_dword v59, v[16:17], off nt
	v_addc_co_u32_e32 v19, vcc, 0, v15, vcc
	v_add_co_u32_e32 v16, vcc, 0x5c000, v14
	s_nop 1
	v_addc_co_u32_e32 v17, vcc, 0, v15, vcc
	v_add_co_u32_e32 v20, vcc, 0x60000, v14
	global_load_dword v60, v[18:19], off nt
	global_load_dword v61, v[16:17], off nt
	v_addc_co_u32_e32 v21, vcc, 0, v15, vcc
	v_add_co_u32_e32 v16, vcc, 0x64000, v14
	s_nop 1
	v_addc_co_u32_e32 v17, vcc, 0, v15, vcc
	v_add_co_u32_e32 v18, vcc, 0x68000, v14
	global_load_dword v62, v[20:21], off nt
	global_load_dword v63, v[16:17], off nt
	v_addc_co_u32_e32 v19, vcc, 0, v15, vcc
	v_add_co_u32_e32 v16, vcc, 0x6c000, v14
	s_nop 1
	v_addc_co_u32_e32 v17, vcc, 0, v15, vcc
	v_add_co_u32_e32 v20, vcc, 0x70000, v14
	global_load_dword v64, v[18:19], off nt
	global_load_dword v65, v[16:17], off nt
	v_addc_co_u32_e32 v21, vcc, 0, v15, vcc
	v_add_co_u32_e32 v16, vcc, 0x74000, v14
	s_nop 1
	v_addc_co_u32_e32 v17, vcc, 0, v15, vcc
	v_add_co_u32_e32 v18, vcc, 0x78000, v14
	global_load_dword v66, v[20:21], off nt
	global_load_dword v67, v[16:17], off nt
	v_addc_co_u32_e32 v19, vcc, 0, v15, vcc
	v_add_co_u32_e32 v14, vcc, 0x7c000, v14
	s_nop 1
	v_addc_co_u32_e32 v15, vcc, 0, v15, vcc
	global_load_dword v68, v[18:19], off nt
	global_load_dword v69, v[14:15], off nt
	global_load_dword v120, v[14:15], off nt
	global_load_dword v120, v[14:15], off nt
	global_load_dword v120, v[14:15], off nt
	global_load_dword v120, v[14:15], off nt
	v_sub_u32_e32 v14, v22, v2
	v_ashrrev_i32_e32 v15, 4, v14
	v_add_u32_e32 v17, 32, v14
	v_and_b32_e32 v14, -2, v15
	v_ashrrev_i32_e32 v19, 4, v17
	v_or_b32_e32 v16, 1, v15
	v_ashrrev_i32_e32 v15, 31, v14
	v_and_b32_e32 v18, -2, v19
	v_ashrrev_i32_e32 v17, 31, v16
	v_or_b32_e32 v20, 1, v19
	v_lshlrev_b64 v[14:15], 17, v[14:15]
	v_ashrrev_i32_e32 v19, 31, v18
	v_lshlrev_b64 v[16:17], 17, v[16:17]
	v_lshl_add_u64 v[32:33], v[30:31], 0, v[14:15]
	v_lshlrev_b64 v[14:15], 17, v[18:19]
	v_lshl_add_u64 v[34:35], v[30:31], 0, v[16:17]
	v_lshl_add_u64 v[38:39], v[30:31], 0, v[14:15]
	s_waitcnt vmcnt(34)
	v_cvt_pk_bf16_f32 v14, v23, v24
	s_waitcnt vmcnt(32)
	v_cvt_pk_bf16_f32 v15, v25, v26
	s_waitcnt vmcnt(30)
	v_cvt_pk_bf16_f32 v16, v27, v28
	s_waitcnt vmcnt(28)
	v_cvt_pk_bf16_f32 v17, v29, v40
	ds_write_b128 v45, v[14:17]
	s_waitcnt vmcnt(26)
	v_cvt_pk_bf16_f32 v14, v41, v42
	s_waitcnt vmcnt(24)
	v_cvt_pk_bf16_f32 v15, v43, v49
	s_waitcnt vmcnt(22)
	v_cvt_pk_bf16_f32 v16, v50, v51
	s_waitcnt vmcnt(20)
	v_cvt_pk_bf16_f32 v17, v52, v53
	ds_write_b128 v45, v[14:17] offset:16
	s_waitcnt vmcnt(18)
	v_cvt_pk_bf16_f32 v14, v54, v55
	s_waitcnt vmcnt(16)
	v_cvt_pk_bf16_f32 v15, v56, v57
	v_ashrrev_i32_e32 v21, 31, v20
	v_lshlrev_b64 v[36:37], 17, v[20:21]
	s_waitcnt vmcnt(14)
	v_cvt_pk_bf16_f32 v16, v58, v59
	v_lshl_add_u64 v[30:31], v[30:31], 0, v[36:37]
	v_cmp_lt_u32_e32 vcc, s66, v13
	s_or_b64 s[46:47], vcc, s[46:47]
	s_waitcnt vmcnt(12)
	v_cvt_pk_bf16_f32 v17, v60, v61
	ds_write_b128 v46, v[14:17]
	s_waitcnt vmcnt(10)
	v_cvt_pk_bf16_f32 v14, v62, v63
	s_waitcnt vmcnt(8)
	v_cvt_pk_bf16_f32 v15, v64, v65
	s_waitcnt vmcnt(6)
	v_cvt_pk_bf16_f32 v16, v66, v67
	s_waitcnt vmcnt(4)
	v_cvt_pk_bf16_f32 v17, v68, v69
	ds_write_b128 v46, v[14:17] offset:16
	ds_read_b128 v[14:17], v47
	ds_read_b128 v[18:21], v47 offset:1024
	ds_read_b128 v[22:25], v47 offset:2048
	ds_read_b128 v[26:29], v47 offset:3072
	s_waitcnt lgkmcnt(3)
	global_store_dwordx4 v[32:33], v[14:17], off
	s_waitcnt lgkmcnt(2)
	global_store_dwordx4 v[34:35], v[18:21], off
	s_waitcnt lgkmcnt(1)
	global_store_dwordx4 v[38:39], v[22:25], off
	s_waitcnt lgkmcnt(0)
	global_store_dwordx4 v[30:31], v[26:29], off
	s_waitcnt lgkmcnt(0)
	s_andn2_b64 exec, exec, s[46:47]
	s_cbranch_execnz .LBB0_45

; template <int MODE, int K, int N>
; __device__ __forceinline__ void conv_blocked(const float* __restrict__ W, bf16* D, const float* __restrict__ gk, unsigned gtid, unsigned nthr, LAS unsigned char* scr  ) {
;     ...
;         if (MODE == 1 && n >= C_U && n < C_GB) continue;
;         const float* src = W + (size_t)k0 * N + n;
;         float v[32];
; #pragma unroll
;         for (int i = 0; i < 32; ++i) v[i] = __builtin_nontemporal_load(src + (size_t)i * N);
.Lsent4_nogk:
	global_load_dword v120, v[58:59], off nt
	global_load_dword v120, v[58:59], off nt
	global_load_dword v120, v[58:59], off nt
	global_load_dword v120, v[58:59], off nt
	s_branch .LBB0_54

; template <int MODE, int K, int N>
; __device__ __forceinline__ void conv_blocked(const float* __restrict__ W, bf16* D, const float* __restrict__ gk, unsigned gtid, unsigned nthr, LAS unsigned char* scr  ) {
;     ...
;         const unsigned kb = it / (unsigned)N; const int n = (int)(it - kb * (unsigned)N), k0 = (int)kb * 32;
;         if (MODE == 1 && n >= C_U && n < C_GB) continue;
;         const float* src = W + (size_t)k0 * N + n;
;         float v[32];
; #pragma unroll
;         for (int i = 0; i < 32; ++i) v[i] = __builtin_nontemporal_load(src + (size_t)i * N);
;         if (gk) {
; #pragma unroll
;             for (int i = 0; i < 32; ++i) v[i] *= gk[k0 + i];
;         }
.LBB0_51:
	v_mul_hi_u32 v6, v42, s67
	v_lshrrev_b32_e32 v43, 13, v6
	v_mad_i32_i24 v10, v43, s68, v42
	v_add_u32_e32 v6, 0xffffe680, v10
	v_cmp_lt_u32_e32 vcc, s69, v6
	s_and_saveexec_b64 s[52:53], vcc
	s_cbranch_execz .LBB0_50
	v_mul_u32_u24_e32 v6, 0x50000, v43
	v_lshl_add_u64 v[12:13], v[6:7], 2, s[46:47]
	v_ashrrev_i32_e32 v11, 31, v10
	v_lshl_add_u64 v[34:35], v[10:11], 2, v[12:13]
	v_add_co_u32_e32 v12, vcc, 0xa000, v34
	s_nop 1
	v_addc_co_u32_e32 v13, vcc, 0, v35, vcc
	v_add_co_u32_e32 v14, vcc, 0x14000, v34
	s_nop 1
	v_addc_co_u32_e32 v15, vcc, 0, v35, vcc
	v_add_co_u32_e32 v16, vcc, 0x1e000, v34
	s_nop 1
	v_addc_co_u32_e32 v17, vcc, 0, v35, vcc
	v_add_co_u32_e32 v18, vcc, 0x28000, v34
	s_nop 1
	v_addc_co_u32_e32 v19, vcc, 0, v35, vcc
	v_add_co_u32_e32 v20, vcc, 0x32000, v34
	s_nop 1
	v_addc_co_u32_e32 v21, vcc, 0, v35, vcc
	v_add_co_u32_e32 v22, vcc, 0x3c000, v34
	s_nop 1
	v_addc_co_u32_e32 v23, vcc, 0, v35, vcc
	v_add_co_u32_e32 v24, vcc, 0x46000, v34
	s_nop 1
	v_addc_co_u32_e32 v25, vcc, 0, v35, vcc
	global_load_dword v10, v[34:35], off nt
	global_load_dword v11, v[12:13], off nt
	s_nop 0
	global_load_dword v12, v[14:15], off nt
	global_load_dword v13, v[16:17], off nt
	s_nop 0
	global_load_dword v14, v[18:19], off nt
	global_load_dword v15, v[20:21], off nt
	global_load_dword v16, v[22:23], off nt
	global_load_dword v17, v[24:25], off nt
	v_add_co_u32_e32 v18, vcc, 0x50000, v34
	s_nop 1
	v_addc_co_u32_e32 v19, vcc, 0, v35, vcc
	v_add_co_u32_e32 v20, vcc, 0x5a000, v34
	s_nop 1
	v_addc_co_u32_e32 v21, vcc, 0, v35, vcc
	v_add_co_u32_e32 v22, vcc, 0x64000, v34
	s_nop 1
	v_addc_co_u32_e32 v23, vcc, 0, v35, vcc
	v_add_co_u32_e32 v24, vcc, 0x6e000, v34
	s_nop 1
	v_addc_co_u32_e32 v25, vcc, 0, v35, vcc
	v_add_co_u32_e32 v26, vcc, 0x78000, v34
	s_nop 1
	v_addc_co_u32_e32 v27, vcc, 0, v35, vcc
	v_add_co_u32_e32 v28, vcc, 0x82000, v34
	s_nop 1
	v_addc_co_u32_e32 v29, vcc, 0, v35, vcc
	v_add_co_u32_e32 v30, vcc, 0x8c000, v34
	s_nop 1
	v_addc_co_u32_e32 v31, vcc, 0, v35, vcc
	v_add_co_u32_e32 v32, vcc, 0x96000, v34
	s_nop 1
	v_addc_co_u32_e32 v33, vcc, 0, v35, vcc
	global_load_dword v18, v[18:19], off nt
	s_nop 0
	global_load_dword v19, v[20:21], off nt
	s_nop 0
	global_load_dword v20, v[22:23], off nt
	global_load_dword v21, v[24:25], off nt
	s_nop 0
	global_load_dword v22, v[26:27], off nt
	global_load_dword v23, v[28:29], off nt
	global_load_dword v24, v[30:31], off nt
	global_load_dword v25, v[32:33], off nt
	v_add_co_u32_e32 v26, vcc, s64, v34
	s_nop 1
	v_addc_co_u32_e32 v27, vcc, 0, v35, vcc
	v_add_co_u32_e32 v28, vcc, 0xaa000, v34
	s_nop 1
	v_addc_co_u32_e32 v29, vcc, 0, v35, vcc
	v_add_co_u32_e32 v30, vcc, 0xb4000, v34
	s_nop 1
	v_addc_co_u32_e32 v31, vcc, 0, v35, vcc
	v_add_co_u32_e32 v32, vcc, 0xbe000, v34
	s_nop 1
	v_addc_co_u32_e32 v33, vcc, 0, v35, vcc
	v_add_co_u32_e32 v36, vcc, 0xc8000, v34
	s_nop 1
	v_addc_co_u32_e32 v37, vcc, 0, v35, vcc
	v_add_co_u32_e32 v38, vcc, 0xd2000, v34
	s_nop 1
	v_addc_co_u32_e32 v39, vcc, 0, v35, vcc
	v_add_co_u32_e32 v40, vcc, 0xdc000, v34
	s_nop 1
	v_addc_co_u32_e32 v41, vcc, 0, v35, vcc
	v_add_co_u32_e32 v50, vcc, 0xe6000, v34
	s_nop 1
	v_addc_co_u32_e32 v51, vcc, 0, v35, vcc
	global_load_dword v26, v[26:27], off nt
	s_nop 0
	global_load_dword v27, v[28:29], off nt
	s_nop 0
	global_load_dword v28, v[30:31], off nt
	global_load_dword v29, v[32:33], off nt
	s_nop 0
	global_load_dword v30, v[36:37], off nt
	global_load_dword v31, v[38:39], off nt
	global_load_dword v32, v[40:41], off nt
	global_load_dword v33, v[50:51], off nt
	v_add_co_u32_e32 v36, vcc, s65, v34
	s_nop 1
	v_addc_co_u32_e32 v37, vcc, 0, v35, vcc
	v_add_co_u32_e32 v38, vcc, 0xfa000, v34
	s_nop 1
	v_addc_co_u32_e32 v39, vcc, 0, v35, vcc
	v_add_co_u32_e32 v40, vcc, 0x104000, v34
	s_nop 1
	v_addc_co_u32_e32 v41, vcc, 0, v35, vcc
	v_add_co_u32_e32 v50, vcc, 0x10e000, v34
	s_nop 1
	v_addc_co_u32_e32 v51, vcc, 0, v35, vcc
	v_add_co_u32_e32 v52, vcc, 0x118000, v34
	s_nop 1
	v_addc_co_u32_e32 v53, vcc, 0, v35, vcc
	v_add_co_u32_e32 v54, vcc, 0x122000, v34
	s_nop 1
	v_addc_co_u32_e32 v55, vcc, 0, v35, vcc
	v_add_co_u32_e32 v56, vcc, 0x12c000, v34
	s_nop 1
	v_addc_co_u32_e32 v57, vcc, 0, v35, vcc
	v_add_co_u32_e32 v58, vcc, 0x136000, v34
	s_nop 1
	v_addc_co_u32_e32 v59, vcc, 0, v35, vcc
	global_load_dword v34, v[36:37], off nt
	global_load_dword v35, v[38:39], off nt
	s_nop 0
	global_load_dword v36, v[40:41], off nt
	global_load_dword v37, v[50:51], off nt
	s_nop 0
	global_load_dword v40, v[52:53], off nt
	global_load_dword v41, v[54:55], off nt
	global_load_dword v38, v[56:57], off nt
	global_load_dword v39, v[58:59], off nt
	s_andn2_b64 vcc, exec, s[34:35]
	s_cbranch_vccnz .Lsent4_nogk
	v_lshlrev_b32_e32 v6, 7, v43
	global_load_dwordx4 v[50:53], v6, s[48:49]
	global_load_dwordx4 v[54:57], v6, s[48:49] offset:16
	global_load_dwordx4 v[58:61], v6, s[48:49] offset:32
	global_load_dwordx4 v[62:65], v6, s[48:49] offset:48
	global_load_dwordx4 v[66:69], v6, s[48:49] offset:64
	global_load_dwordx4 v[70:73], v6, s[48:49] offset:80
	global_load_dwordx4 v[74:77], v6, s[48:49] offset:96
	global_load_dwordx4 v[78:81], v6, s[48:49] offset:112
	global_load_dword v120, v6, s[48:49]
	global_load_dword v120, v6, s[48:49]
	global_load_dword v120, v6, s[48:49]
	global_load_dword v120, v6, s[48:49]
	s_waitcnt vmcnt(11)
	v_pk_mul_f32 v[10:11], v[10:11], v[50:51]
	v_pk_mul_f32 v[12:13], v[12:13], v[52:53]
	s_waitcnt vmcnt(10)
	v_pk_mul_f32 v[14:15], v[14:15], v[54:55]
	v_pk_mul_f32 v[16:17], v[16:17], v[56:57]
	s_waitcnt vmcnt(9)
	v_pk_mul_f32 v[18:19], v[18:19], v[58:59]
	v_pk_mul_f32 v[20:21], v[20:21], v[60:61]
	s_waitcnt vmcnt(8)
	v_pk_mul_f32 v[22:23], v[22:23], v[62:63]
	v_pk_mul_f32 v[24:25], v[24:25], v[64:65]
	s_waitcnt vmcnt(7)
	v_pk_mul_f32 v[26:27], v[26:27], v[66:67]
	v_pk_mul_f32 v[28:29], v[28:29], v[68:69]
	s_waitcnt vmcnt(6)
	v_pk_mul_f32 v[30:31], v[30:31], v[70:71]
	v_pk_mul_f32 v[32:33], v[32:33], v[72:73]
	s_waitcnt vmcnt(5)
	v_pk_mul_f32 v[34:35], v[34:35], v[74:75]
	v_pk_mul_f32 v[36:37], v[36:37], v[76:77]
	s_waitcnt vmcnt(4)
	v_pk_mul_f32 v[40:41], v[40:41], v[78:79]
	v_pk_mul_f32 v[38:39], v[38:39], v[80:81]
; __device__ __forceinline__ unsigned cvt_pk_bf16(float lo, float hi) { f32x2 v = {lo, hi}; bf16x2_t b = __builtin_convertvector(v, bf16x2_t); return __builtin_bit_cast(unsigned, b); }
; #define LAS __attribute__((address_space(3)))
; __device__ __forceinline__ int nperm(int n) {
;     const int tile = n >> 8, c = n & 255; int cp = c;
;     if (tile < 8) { const int q = c >> 6, i = c & 63; cp = (i < 32) ? 32 * q + i : 128 + 32 * q + (i - 32); }
;     else if (tile >= 12 && tile <= 20) { const int u = c >> 7, i = c & 127; cp = (i < 64) ? 64 * u + i : 128 + 64 * u + (i - 64); }
;     return tile * 256 + cp;
; template <int MODE, int K, int N>
; __device__ __forceinline__ void conv_blocked(const float* __restrict__ W, bf16* D, const float* __restrict__ gk, unsigned gtid, unsigned nthr, LAS unsigned char* scr  ) {
;     ...
;         const int rho = pg8::p32inv(lane & 31), half = lane >> 5;
; #pragma unroll
;         for (int c = 0; c < 4; ++c) { v4u o; o.x = cvt_pk_bf16(v[8 * c], v[8 * c + 1]); o.y = cvt_pk_bf16(v[8 * c + 2], v[8 * c + 3]); o.z = cvt_pk_bf16(v[8 * c + 4], v[8 * c + 5]); o.w = cvt_pk_bf16(v[8 * c + 6], v[8 * c + 7]);
;             *(LAS v4u*)(scr + (half * 32 + rho) * 64 + ((c * 16) ^ ((rho & 8) << 2))) = o; }
;         const int nb = n - lane;
; #pragma unroll
;         for (int i = 0; i < 4; ++i) { const int h2 = i >> 1, b2 = i & 1; const int gp = ((MODE == 1) ? nperm(nb + 32 * h2) : nb + 32 * h2) & ~31;
;             const v4u o = *(const LAS v4u*)(scr + (h2 * 32 + b2 * 16) * 64 + lane * 16);
.LBB0_54:
	s_waitcnt vmcnt(34)
	v_cvt_pk_bf16_f32 v10, v10, v11
	s_waitcnt vmcnt(32)
	v_cvt_pk_bf16_f32 v11, v12, v13
	s_waitcnt vmcnt(30)
	v_cvt_pk_bf16_f32 v12, v14, v15
	s_waitcnt vmcnt(28)
	v_cvt_pk_bf16_f32 v13, v16, v17
	ds_write_b128 v45, v[10:13]
	s_waitcnt vmcnt(26)
	v_cvt_pk_bf16_f32 v10, v18, v19
	s_waitcnt vmcnt(24)
	v_cvt_pk_bf16_f32 v11, v20, v21
	s_waitcnt vmcnt(22)
	v_cvt_pk_bf16_f32 v12, v22, v23
	s_waitcnt vmcnt(20)
	v_cvt_pk_bf16_f32 v13, v24, v25
	ds_write_b128 v45, v[10:13] offset:16
	s_waitcnt vmcnt(18)
	v_cvt_pk_bf16_f32 v10, v26, v27
	s_waitcnt vmcnt(16)
	v_cvt_pk_bf16_f32 v11, v28, v29
	s_waitcnt vmcnt(14)
	v_cvt_pk_bf16_f32 v12, v30, v31
	s_waitcnt vmcnt(12)
	v_cvt_pk_bf16_f32 v13, v32, v33
	v_mul_i32_i24_e32 v6, 0xffffd800, v43
	ds_write_b128 v46, v[10:13]
	s_waitcnt vmcnt(10)
	v_cvt_pk_bf16_f32 v10, v34, v35
	s_waitcnt vmcnt(8)
	v_cvt_pk_bf16_f32 v11, v36, v37
	s_waitcnt vmcnt(6)
	v_cvt_pk_bf16_f32 v12, v40, v41
	s_waitcnt vmcnt(4)
	v_cvt_pk_bf16_f32 v13, v38, v39
	ds_write_b128 v46, v[10:13] offset:16
	v_add3_u32 v12, v44, v6, v42
	v_ashrrev_i32_e32 v6, 8, v12
	v_cmp_lt_i32_e32 vcc, 7, v6
	v_add_u32_e32 v14, -12, v6
	v_and_b32_e32 v13, 0xff, v12
	s_and_saveexec_b64 s[2:3], vcc
	s_xor_b64 s[2:3], exec, s[2:3]
	s_cbranch_execz .LBB0_62
	v_and_b32_e32 v17, 0xff, v12
	v_cmp_gt_u32_e64 s[10:11], 9, v14
	s_and_saveexec_b64 s[54:55], s[10:11]
	s_cbranch_execz .LBB0_61
	v_and_b32_e32 v6, 0x7f, v12
	v_lshrrev_b32_e32 v10, 1, v12
	v_cmp_lt_u32_e64 s[10:11], 63, v6
	v_and_b32_e32 v10, 64, v10
	s_and_saveexec_b64 s[72:73], s[10:11]
	s_xor_b64 s[10:11], exec, s[72:73]
	v_add3_u32 v17, v6, v10, 64
	s_andn2_saveexec_b64 s[10:11], s[10:11]
	v_or_b32_e32 v17, v10, v6
	s_or_b64 exec, exec, s[10:11]
